# PLEGATE epilogue first wait counted (it=1 loads stay in flight); canonicalizing v_max triples folded in attention loops
# speedup vs baseline: 1.0017x; 1.0008x over previous
; template <int EPI>
; __device__ __forceinline__ void gemm_epilogue(const f32x4 (&acc)[2][2][4][2], const Unit& u, int wr, int wc, int fr, int fq,
;                                               const EpiArgs& ea, const float (&rs_pre)[2][4]) {
;     ...
;     EPI_LOAD_ROW(0, hc, lc, pc);
; #pragma unroll
;     for (int it = 0; it < 8; ++it) {
;       const int ai = it >> 2, m = it & 3;
;       if (it + 1 < 8) EPI_LOAD_ROW(it + 1, hn, ln_, pq);
;       const int row = row0 + ai * 128 + m * 16;
;       float sq = 0.f;
; #pragma unroll
;       for (int bj = 0; bj < 2; ++bj) {
;         const size_t idx = (size_t)row * 1024 + lcp + bj * 32;
;         const uint32_t hw[4] = {hc[bj].x, hc[bj].y, hc[bj].z, hc[bj].w};
;         const uint32_t lw[4] = {lc[bj].x, lc[bj].y, lc[bj].z, lc[bj].w};
;         const uint32_t pw[4] = {pc[bj].x, pc[bj].y, pc[bj].z, pc[bj].w};
;         uint32_t ho[4], lo_[4];
; #pragma unroll
;         for (int n = 0; n < 2; ++n) {
;           f32x4 xv;
;           xv[0] = __uint_as_float(hw[2 * n] << 16) + __uint_as_float(lw[2 * n] << 16);
;           xv[1] = __uint_as_float(hw[2 * n] & 0xffff0000u) + __uint_as_float(lw[2 * n] & 0xffff0000u);
;           xv[2] = __uint_as_float(hw[2 * n + 1] << 16) + __uint_as_float(lw[2 * n + 1] << 16);
;           xv[3] = __uint_as_float(hw[2 * n + 1] & 0xffff0000u) + __uint_as_float(lw[2 * n + 1] & 0xffff0000u);
;           const f32x4 a = acc[ai][bj][m][n];
;           f32x4 v;
;           if constexpr (EPI == EPI_PLEGATE) {
;             const float rs = rsr[ai][m], rpe = rper[ai][m];
;             const float pv[4] = {__uint_as_float(pw[2 * n] << 16), __uint_as_float(pw[2 * n] & 0xffff0000u),
;                                  __uint_as_float(pw[2 * n + 1] << 16), __uint_as_float(pw[2 * n + 1] & 0xffff0000u)};
; #pragma unroll
;             for (int i = 0; i < 4; ++i) v[i] = xv[i] + sigmoidf_(a[i] * rs) * (pv[i] * rpe);
;           } else {
;             v = xv + a * ea.alpha;
;           }
;           const uint2 hnew = pack4(v);
;           ho[2 * n] = hnew.x; ho[2 * n + 1] = hnew.y;
;           if (ea.xf32_out) {
;             *reinterpret_cast<f32x4*>(ea.xf32_out + idx + 4 * n) = v;
;           } else {
;             f32x4 r;
;             r[0] = v[0] - __uint_as_float(hnew.x << 16);
;             r[1] = v[1] - __uint_as_float(hnew.x & 0xffff0000u);
.LBB0_176:
	v_lshl_add_u32 v196, s14, 8, v182
	v_ashrrev_i32_e32 v197, 31, v196
	v_readlane_b32 s4, v254, 42
	v_lshl_add_u32 v194, s2, 8, v208
	v_readlane_b32 s5, v254, 43
	v_lshlrev_b64 v[132:133], 10, v[196:197]
	v_ashrrev_i32_e32 v195, 31, v194
	v_lshl_add_u64 v[114:115], v[196:197], 2, s[4:5]
	v_lshl_add_u64 v[206:207], v[132:133], 0, v[194:195]
	global_load_dword v168, v[114:115], off
	v_lshlrev_b64 v[204:205], 1, v[206:207]
	v_readlane_b32 s4, v251, 32
	v_lshl_add_u64 v[132:133], s[46:47], 0, v[204:205]
	v_readlane_b32 s5, v251, 33
	v_or_b32_e32 v198, 16, v196
	v_lshl_add_u64 v[134:135], s[18:19], 0, v[204:205]
	global_load_dwordx4 v[174:177], v[132:133], off
	global_load_dwordx4 v[178:181], v[134:135], off
	global_load_dword v240, v[114:115], off offset:64
	global_load_dword v239, v[114:115], off offset:128
	global_load_dword v238, v[114:115], off offset:192
	global_load_dword v237, v[114:115], off offset:512
	global_load_dword v235, v[114:115], off offset:576
	global_load_dword v216, v[114:115], off offset:640
	global_load_dword v214, v[114:115], off offset:704
	v_lshl_add_u64 v[114:115], s[4:5], 0, v[204:205]
	v_ashrrev_i32_e32 v199, 31, v198
	global_load_dwordx4 v[170:173], v[114:115], off
	global_load_dwordx4 v[160:163], v[132:133], off offset:64
	global_load_dwordx4 v[164:167], v[134:135], off offset:64
	global_load_dwordx4 v[156:159], v[114:115], off offset:64
	v_lshlrev_b64 v[114:115], 10, v[198:199]
	v_lshl_add_u64 v[202:203], v[114:115], 0, v[194:195]
	v_lshlrev_b64 v[200:201], 1, v[202:203]
	v_lshl_add_u64 v[114:115], s[46:47], 0, v[200:201]
	v_lshl_add_u64 v[132:133], s[18:19], 0, v[200:201]
	v_lshl_add_u64 v[134:135], s[4:5], 0, v[200:201]
	global_load_dwordx4 v[148:151], v[114:115], off
	global_load_dwordx4 v[136:139], v[114:115], off offset:64
	global_load_dwordx4 v[152:155], v[132:133], off
	global_load_dwordx4 v[140:143], v[132:133], off offset:64
	global_load_dwordx4 v[144:147], v[134:135], off
	s_nop 0
	global_load_dwordx4 v[132:135], v[134:135], off offset:64
	s_waitcnt vmcnt(6)
	v_fmamk_f32 v113, v113, 0x3a800000, v218
	v_mul_f32_e32 v114, 0x4b800000, v113
	v_cmp_gt_f32_e32 vcc, s26, v113
	v_readlane_b32 s8, v254, 50
	v_readlane_b32 s9, v254, 51
	v_cndmask_b32_e32 v113, v113, v114, vcc
	v_rsq_f32_e32 v113, v113
	v_cndmask_b32_e64 v114, 0, 1, s[8:9]
	v_cmp_ne_u32_e64 s[4:5], 1, v114
	s_mov_b64 s[36:37], -1
	v_mul_f32_e32 v114, 0x45800000, v113
	v_cndmask_b32_e32 v241, v113, v114, vcc
	v_mul_f32_e32 v36, v241, v36
	v_mul_f32_e32 v37, v241, v37
	v_mul_f32_e32 v38, v241, v38
	v_mul_f32_e32 v39, v241, v39
	v_mul_f32_e32 v36, 0xbfb8aa3b, v36
	v_mul_f32_e32 v37, 0xbfb8aa3b, v37
	v_mul_f32_e32 v38, 0xbfb8aa3b, v38
	v_mul_f32_e32 v39, 0xbfb8aa3b, v39
	v_exp_f32_e32 v36, v36
	v_exp_f32_e32 v37, v37
	v_exp_f32_e32 v38, v38
	v_exp_f32_e32 v39, v39
	v_add_f32_e32 v36, 1.0, v36
	v_add_f32_e32 v37, 1.0, v37
	v_add_f32_e32 v38, 1.0, v38
	v_add_f32_e32 v39, 1.0, v39
	v_rcp_f32_e32 v36, v36
	v_rcp_f32_e32 v37, v37
	v_rcp_f32_e32 v38, v38
	v_rcp_f32_e32 v39, v39
	v_and_b32_e32 v115, 0xffff0000, v174
	v_fmamk_f32 v113, v168, 0x3a800000, v218
	v_mul_f32_e32 v114, 0x4b800000, v113
	v_cmp_gt_f32_e32 vcc, s26, v113
	v_lshlrev_b32_e32 v168, 16, v178
	v_and_b32_e32 v169, 0xffff0000, v178
	v_cndmask_b32_e32 v113, v113, v114, vcc
	v_rsq_f32_e32 v113, v113
	v_lshlrev_b32_e32 v114, 16, v174
	v_lshlrev_b32_e32 v174, 16, v175
	v_lshlrev_b32_e32 v178, 16, v179
	v_and_b32_e32 v175, 0xffff0000, v175
	v_and_b32_e32 v179, 0xffff0000, v179
	v_pk_add_f32 v[114:115], v[114:115], v[168:169]
	v_mul_f32_e32 v168, 0x45800000, v113
	v_lshlrev_b32_e32 v242, 16, v170
	v_and_b32_e32 v243, 0xffff0000, v170
	v_lshlrev_b32_e32 v170, 16, v171
	v_and_b32_e32 v171, 0xffff0000, v171
	v_pk_add_f32 v[174:175], v[174:175], v[178:179]
	v_cndmask_b32_e32 v178, v113, v168, vcc
	v_pk_mul_f32 v[168:169], v[178:179], v[242:243] op_sel_hi:[0,1]
	v_pk_mul_f32 v[170:171], v[178:179], v[170:171] op_sel_hi:[0,1]
	v_pk_fma_f32 v[168:169], v[36:37], v[168:169], v[114:115]
	v_pk_fma_f32 v[170:171], v[38:39], v[170:171], v[174:175]
	s_andn2_b64 vcc, exec, s[8:9]
	v_cvt_pk_bf16_f32 v174, v168, v169
	v_cvt_pk_bf16_f32 v175, v170, v171
	s_cbranch_vccnz .LBB0_178
	v_lshl_add_u64 v[36:37], v[206:207], 2, s[88:89]
	s_mov_b64 s[36:37], 0
	s_mov_b64 s[8:9], s[88:89]
	global_store_dwordx4 v[36:37], v[168:171], off

; template <int EPI>
; __device__ __forceinline__ void gemm_epilogue(const f32x4 (&acc)[2][2][4][2], const Unit& u, int wr, int wc, int fr, int fq,
;                                               const EpiArgs& ea, const float (&rs_pre)[2][4]) {
;     ...
;     EPI_LOAD_ROW(0, hc, lc, pc);
; #pragma unroll
;     for (int it = 0; it < 8; ++it) {
;       const int ai = it >> 2, m = it & 3;
;       if (it + 1 < 8) EPI_LOAD_ROW(it + 1, hn, ln_, pq);
;       const int row = row0 + ai * 128 + m * 16;
;       float sq = 0.f;
; #pragma unroll
;       for (int bj = 0; bj < 2; ++bj) {
;         const size_t idx = (size_t)row * 1024 + lcp + bj * 32;
;         const uint32_t hw[4] = {hc[bj].x, hc[bj].y, hc[bj].z, hc[bj].w};
;         const uint32_t lw[4] = {lc[bj].x, lc[bj].y, lc[bj].z, lc[bj].w};
;         const uint32_t pw[4] = {pc[bj].x, pc[bj].y, pc[bj].z, pc[bj].w};
;         uint32_t ho[4], lo_[4];
; #pragma unroll
;         for (int n = 0; n < 2; ++n) {
;           f32x4 xv;
;           xv[0] = __uint_as_float(hw[2 * n] << 16) + __uint_as_float(lw[2 * n] << 16);
;           xv[1] = __uint_as_float(hw[2 * n] & 0xffff0000u) + __uint_as_float(lw[2 * n] & 0xffff0000u);
;           xv[2] = __uint_as_float(hw[2 * n + 1] << 16) + __uint_as_float(lw[2 * n + 1] << 16);
;           xv[3] = __uint_as_float(hw[2 * n + 1] & 0xffff0000u) + __uint_as_float(lw[2 * n + 1] & 0xffff0000u);
;           const f32x4 a = acc[ai][bj][m][n];
;           f32x4 v;
;           if constexpr (EPI == EPI_PLEGATE) {
;             const float rs = rsr[ai][m], rpe = rper[ai][m];
;             const float pv[4] = {__uint_as_float(pw[2 * n] << 16), __uint_as_float(pw[2 * n] & 0xffff0000u),
;                                  __uint_as_float(pw[2 * n + 1] << 16), __uint_as_float(pw[2 * n + 1] & 0xffff0000u)};
; #pragma unroll
;             for (int i = 0; i < 4; ++i) v[i] = xv[i] + sigmoidf_(a[i] * rs) * (pv[i] * rpe);
;           } else {
;             v = xv + a * ea.alpha;
;           }
;           const uint2 hnew = pack4(v);
;           ho[2 * n] = hnew.x; ho[2 * n + 1] = hnew.y;
;           if (ea.xf32_out) {
;             *reinterpret_cast<f32x4*>(ea.xf32_out + idx + 4 * n) = v;
;           } else {
;             f32x4 r;
;             r[0] = v[0] - __uint_as_float(hnew.x << 16);
;             r[1] = v[1] - __uint_as_float(hnew.x & 0xffff0000u);
.LBB0_200:
	s_waitcnt vmcnt(4)
	s_or_b64 exec, exec, s[8:9]
	v_or_b32_e32 v168, 32, v196
	v_ashrrev_i32_e32 v169, 31, v168
	v_lshlrev_b64 v[114:115], 10, v[168:169]
	v_lshl_add_u64 v[172:173], v[114:115], 0, v[194:195]
	v_readlane_b32 s8, v251, 32
	v_lshlrev_b64 v[170:171], 1, v[172:173]
	v_readlane_b32 s9, v251, 33
	v_lshl_add_u64 v[114:115], s[46:47], 0, v[170:171]
	v_lshl_add_u64 v[120:121], s[18:19], 0, v[170:171]
	v_lshl_add_u64 v[122:123], s[8:9], 0, v[170:171]
	global_load_dwordx4 v[160:163], v[114:115], off
	global_load_dwordx4 v[124:127], v[114:115], off offset:64
	global_load_dwordx4 v[164:167], v[120:121], off
	global_load_dwordx4 v[128:131], v[120:121], off offset:64
	global_load_dwordx4 v[156:159], v[122:123], off
	s_nop 0
	global_load_dwordx4 v[120:123], v[122:123], off offset:64
	v_fmamk_f32 v113, v236, 0x3a800000, v218
	v_mul_f32_e32 v114, 0x4b800000, v113
	v_cmp_gt_f32_e32 vcc, s26, v113
	v_lshlrev_b32_e32 v176, 16, v152
	v_and_b32_e32 v177, 0xffff0000, v152
	v_cndmask_b32_e32 v113, v113, v114, vcc
	v_rsq_f32_e32 v113, v113
	v_fmamk_f32 v114, v240, 0x3a800000, v218
	v_mul_f32_e32 v115, 0x4b800000, v114
	v_cmp_gt_f32_e64 s[8:9], s26, v114
	v_lshlrev_b32_e32 v178, 16, v144
	v_and_b32_e32 v179, 0xffff0000, v144
	v_cndmask_b32_e64 v114, v114, v115, s[8:9]
	v_rsq_f32_e32 v114, v114
	v_mul_f32_e32 v115, 0x45800000, v113
	v_cndmask_b32_e32 v113, v113, v115, vcc
	v_mul_f32_e32 v118, v113, v118
	v_mul_f32_e32 v116, v113, v116
	v_mul_f32_e32 v117, v113, v117
	v_mul_f32_e32 v118, 0xbfb8aa3b, v118
	v_mul_f32_e32 v115, 0x45800000, v114
	v_mul_f32_e32 v116, 0xbfb8aa3b, v116
	v_mul_f32_e32 v117, 0xbfb8aa3b, v117
	v_exp_f32_e32 v175, v118
	v_mul_f32_e32 v118, v113, v119
	v_cndmask_b32_e64 v174, v114, v115, s[8:9]
	v_lshlrev_b32_e32 v114, 16, v148
	v_and_b32_e32 v115, 0xffff0000, v148
	v_exp_f32_e32 v116, v116
	v_exp_f32_e32 v117, v117
	v_mul_f32_e32 v118, 0xbfb8aa3b, v118
	v_pk_add_f32 v[114:115], v[114:115], v[176:177]
	v_exp_f32_e32 v177, v118
	v_add_f32_e32 v116, 1.0, v116
	v_add_f32_e32 v117, 1.0, v117
	v_pk_mul_f32 v[118:119], v[174:175], v[178:179] op_sel_hi:[0,1]
	v_add_f32_e32 v175, 1.0, v175
	v_rcp_f32_e32 v116, v116
	v_rcp_f32_e32 v117, v117
	v_rcp_f32_e32 v176, v175
	v_add_f32_e32 v175, 1.0, v177
	v_rcp_f32_e32 v177, v175
	v_lshlrev_b32_e32 v148, 16, v149
	v_lshlrev_b32_e32 v152, 16, v153
	v_and_b32_e32 v149, 0xffff0000, v149
	v_and_b32_e32 v153, 0xffff0000, v153
	v_lshlrev_b32_e32 v144, 16, v145
	v_and_b32_e32 v145, 0xffff0000, v145
	v_pk_fma_f32 v[114:115], v[116:117], v[118:119], v[114:115]
	v_pk_add_f32 v[116:117], v[148:149], v[152:153]
	v_pk_mul_f32 v[118:119], v[174:175], v[144:145] op_sel_hi:[0,1]
	v_pk_fma_f32 v[116:117], v[176:177], v[118:119], v[116:117]
	s_and_b64 vcc, exec, s[4:5]
	s_mov_b64 s[36:37], -1
	v_cvt_pk_bf16_f32 v144, v114, v115
	v_cvt_pk_bf16_f32 v145, v116, v117
	s_cbranch_vccnz .LBB0_202
	v_lshl_add_u64 v[118:119], v[202:203], 2, s[88:89]
	s_mov_b64 s[36:37], 0
	s_mov_b64 s[8:9], s[88:89]
	global_store_dwordx4 v[118:119], v[114:117], off

; __device__ __forceinline__ float ex2(float x) { return __builtin_amdgcn_exp2f(x); }
; template <bool FOX> ...
;     ...
;     const bool needmask = FOX ? (k0 + 31 > q0) : true;
;     if (needmask) {
; #pragma unroll
;       for (int qt = 0; qt < 2; ++qt) {
;         int qpos = q0 + qt * 32 + ln;
; #pragma unroll
;         for (int r = 0; r < 16; ++r) {
;           int kpos = k0 + 8 * (r >> 2) + 4 * hh + (r & 3);
;           bool bad = kpos > qpos;
;           if (!FOX) bad = bad || (qpos - kpos >= 128);
;           st[qt][r] = bad ? -1e30f : st[qt][r];
;         }
;       }
;     }
;     bf16x8 bp[2][2];
; #pragma unroll
;     for (int qt = 0; qt < 2; ++qt) {
;       float mx = fmaxf(fmaxf(st[qt][0], st[qt][1]), fmaxf(st[qt][2], st[qt][3]));
; #pragma unroll
;       for (int r = 4; r < 16; r += 4) mx = fmaxf(fmaxf(mx, st[qt][r]), fmaxf(fmaxf(st[qt][r + 1], st[qt][r + 2]), st[qt][r + 3]));
;       mx = xmax32(mx);
;       const float mnew = fmaxf(mrun[qt], mx);
;       const float alpha = ex2(mrun[qt] - mnew);
;       mrun[qt] = mnew;
;       float ps0 = 0.f, ps1 = 0.f;
; #pragma unroll
;       for (int r = 0; r < 16; r += 2) {
;         float p0 = ex2(st[qt][r] - mnew), p1 = ex2(st[qt][r + 1] - mnew);
;         ps0 += p0; ps1 += p1;
;         st[qt][r] = p0; st[qt][r + 1] = p1;
;       }
;       lrun[qt] = lrun[qt] * alpha + (ps0 + ps1);
; #pragma unroll
;       for (int dt = 0; dt < 2; ++dt) o[dt][qt] = o[dt][qt] * alpha;
.LBB0_501:
	v_cmp_gt_i32_e32 vcc, v185, v166
	v_cmp_lt_i32_e64 s[0:1], v185, v113
	s_or_b64 vcc, vcc, s[0:1]
	v_add_u32_e32 v174, 1, v185
	s_nop 5
	v_cndmask_b32_e32 v80, v80, v230, vcc
	v_cmp_ge_i32_e32 vcc, v185, v166
	v_cmp_lt_i32_e64 s[0:1], v174, v113
	s_or_b64 vcc, vcc, s[0:1]
	v_add_u32_e32 v175, 2, v185
	v_cndmask_b32_e32 v81, v81, v230, vcc
	v_cmp_gt_i32_e32 vcc, v175, v166
	v_cmp_lt_i32_e64 s[0:1], v175, v113
	s_or_b64 vcc, vcc, s[0:1]
	v_cndmask_b32_e32 v176, v82, v230, vcc
	v_add_u32_e32 v82, 3, v185
	v_cmp_gt_i32_e32 vcc, v82, v166
	v_cmp_lt_i32_e64 s[0:1], v82, v113
	s_or_b64 vcc, vcc, s[0:1]
	v_add_u32_e32 v177, 8, v185
	v_cndmask_b32_e32 v83, v83, v230, vcc
	v_cmp_gt_i32_e32 vcc, v177, v166
	v_cmp_lt_i32_e64 s[0:1], v177, v113
	s_or_b64 vcc, vcc, s[0:1]
	v_cndmask_b32_e32 v178, v84, v230, vcc
	v_add_u32_e32 v84, 9, v185
	v_cmp_gt_i32_e32 vcc, v84, v166
	v_cmp_lt_i32_e64 s[0:1], v84, v113
	s_or_b64 vcc, vcc, s[0:1]
	v_add_u32_e32 v179, 10, v185
	v_cndmask_b32_e32 v85, v85, v230, vcc
	v_cmp_gt_i32_e32 vcc, v179, v166
	v_cmp_lt_i32_e64 s[0:1], v179, v113
	s_or_b64 vcc, vcc, s[0:1]
	v_cndmask_b32_e32 v180, v86, v230, vcc
	v_add_u32_e32 v86, 11, v185
	v_cmp_gt_i32_e32 vcc, v86, v166
	v_cmp_lt_i32_e64 s[0:1], v86, v113
	s_or_b64 vcc, vcc, s[0:1]
	v_add_u32_e32 v181, 16, v185
	v_cndmask_b32_e32 v87, v87, v230, vcc
	v_cmp_gt_i32_e32 vcc, v181, v166
	v_cmp_lt_i32_e64 s[0:1], v181, v113
	s_or_b64 vcc, vcc, s[0:1]
	v_cndmask_b32_e32 v187, v88, v230, vcc
	v_add_u32_e32 v88, 17, v185
	v_cmp_gt_i32_e32 vcc, v88, v166
	v_cmp_lt_i32_e64 s[0:1], v88, v113
	s_or_b64 vcc, vcc, s[0:1]
	v_add_u32_e32 v186, 18, v185
	v_cndmask_b32_e32 v89, v89, v230, vcc
	v_cmp_gt_i32_e32 vcc, v186, v166
	v_cmp_lt_i32_e64 s[0:1], v186, v113
	s_or_b64 vcc, vcc, s[0:1]
	v_add_u32_e32 v188, 19, v185
	v_cndmask_b32_e32 v90, v90, v230, vcc
	v_cmp_gt_i32_e32 vcc, v188, v166
	v_cmp_lt_i32_e64 s[0:1], v188, v113
	s_or_b64 vcc, vcc, s[0:1]
	v_add_u32_e32 v189, 24, v185
	v_cndmask_b32_e32 v91, v91, v230, vcc
	v_cmp_gt_i32_e32 vcc, v189, v166
	v_cmp_lt_i32_e64 s[0:1], v189, v113
	s_or_b64 vcc, vcc, s[0:1]
	v_cndmask_b32_e32 v190, v92, v230, vcc
	v_add_u32_e32 v92, 25, v185
	v_cmp_gt_i32_e32 vcc, v92, v166
	v_cmp_lt_i32_e64 s[0:1], v92, v113
	s_or_b64 vcc, vcc, s[0:1]
	v_add_u32_e32 v191, 26, v185
	v_cndmask_b32_e32 v93, v93, v230, vcc
	v_cmp_gt_i32_e32 vcc, v191, v166
	v_cmp_lt_i32_e64 s[0:1], v191, v113
	s_or_b64 vcc, vcc, s[0:1]
	v_cndmask_b32_e32 v192, v94, v230, vcc
	v_add_u32_e32 v94, 27, v185
	v_cmp_gt_i32_e32 vcc, v94, v166
	v_cmp_lt_i32_e64 s[0:1], v94, v113
	s_or_b64 vcc, vcc, s[0:1]
	v_cndmask_b32_e32 v95, v95, v230, vcc
	v_cmp_gt_i32_e32 vcc, v185, v162
	v_cmp_lt_i32_e64 s[0:1], v185, v169
	s_or_b64 vcc, vcc, s[0:1]
	v_cndmask_b32_e32 v193, v64, v230, vcc
	v_cmp_ge_i32_e32 vcc, v185, v162
	v_cmp_lt_i32_e64 s[0:1], v174, v169
	s_or_b64 vcc, vcc, s[0:1]
	v_cndmask_b32_e32 v194, v65, v230, vcc
	v_cmp_gt_i32_e32 vcc, v175, v162
	v_cmp_lt_i32_e64 s[0:1], v175, v169
	s_or_b64 vcc, vcc, s[0:1]
	v_cndmask_b32_e32 v175, v66, v230, vcc
	v_cmp_gt_i32_e32 vcc, v82, v162
	v_cmp_lt_i32_e64 s[0:1], v82, v169
	s_or_b64 vcc, vcc, s[0:1]
	v_cndmask_b32_e32 v195, v67, v230, vcc
	v_cmp_gt_i32_e32 vcc, v177, v162
	v_cmp_lt_i32_e64 s[0:1], v177, v169
	s_or_b64 vcc, vcc, s[0:1]
	v_cndmask_b32_e32 v177, v68, v230, vcc
	v_cmp_gt_i32_e32 vcc, v84, v162
	v_cmp_lt_i32_e64 s[0:1], v84, v169
	s_or_b64 vcc, vcc, s[0:1]
	v_cndmask_b32_e32 v196, v69, v230, vcc
	v_cmp_gt_i32_e32 vcc, v179, v162
	v_cmp_lt_i32_e64 s[0:1], v179, v169
	s_or_b64 vcc, vcc, s[0:1]
	v_cndmask_b32_e32 v179, v70, v230, vcc
	v_cmp_gt_i32_e32 vcc, v86, v162
	v_cmp_lt_i32_e64 s[0:1], v86, v169
	s_or_b64 vcc, vcc, s[0:1]
	v_cndmask_b32_e32 v197, v71, v230, vcc
	v_cmp_gt_i32_e32 vcc, v181, v162
	v_cmp_lt_i32_e64 s[0:1], v181, v169
	s_or_b64 vcc, vcc, s[0:1]
	v_cndmask_b32_e32 v181, v72, v230, vcc
	v_cmp_gt_i32_e32 vcc, v88, v162
	v_cmp_lt_i32_e64 s[0:1], v88, v169
	s_or_b64 vcc, vcc, s[0:1]
	v_cndmask_b32_e32 v73, v73, v230, vcc
	v_cmp_gt_i32_e32 vcc, v186, v162
	v_cmp_lt_i32_e64 s[0:1], v186, v169
	v_max_f32_e32 v64, v83, v83
	v_max_f32_e32 v65, v176, v176
	s_or_b64 vcc, vcc, s[0:1]
	v_max_f32_e32 v64, v65, v64
	v_cndmask_b32_e32 v198, v74, v230, vcc
	v_cmp_gt_i32_e32 vcc, v188, v162
	v_cmp_lt_i32_e64 s[0:1], v188, v169
	v_max3_f32 v64, v80, v81, v64
	v_max3_f32 v65, v85, v180, v87
	s_or_b64 vcc, vcc, s[0:1]
	v_max3_f32 v64, v64, v178, v65
	v_max3_f32 v65, v89, v90, v91
	v_cndmask_b32_e32 v75, v75, v230, vcc
	v_cmp_gt_i32_e32 vcc, v189, v162
	v_cmp_lt_i32_e64 s[0:1], v189, v169
	v_max3_f32 v64, v64, v187, v65
	v_max3_f32 v65, v93, v192, v95
	s_or_b64 vcc, vcc, s[0:1]
	v_max3_f32 v64, v64, v190, v65
	v_cndmask_b32_e32 v188, v76, v230, vcc
	v_cmp_gt_i32_e32 vcc, v92, v162
	v_cmp_lt_i32_e64 s[0:1], v92, v169
	v_mov_b32_e32 v65, v64
	s_or_b64 vcc, vcc, s[0:1]
	s_nop 0
	v_permlane32_swap_b32_e32 v64, v65
	v_cndmask_b32_e32 v77, v77, v230, vcc
	v_cmp_gt_i32_e32 vcc, v191, v162
	v_cmp_lt_i32_e64 s[0:1], v191, v169
	v_max3_f32 v186, v172, v64, v65
	s_or_b64 vcc, vcc, s[0:1]
	v_sub_f32_e32 v64, v172, v186
	v_cndmask_b32_e32 v189, v78, v230, vcc
	v_exp_f32_e32 v78, v64
	v_cmp_gt_i32_e32 vcc, v94, v162
	v_cmp_lt_i32_e64 s[0:1], v94, v169
	s_or_b64 vcc, vcc, s[0:1]
	v_sub_f32_e32 v65, v80, v186
	v_cndmask_b32_e32 v199, v79, v230, vcc
	v_exp_f32_e32 v80, v65
	v_sub_f32_e32 v65, v81, v186
	v_pk_mul_f32 v[62:63], v[62:63], v[78:79] op_sel_hi:[1,0]
	v_pk_mul_f32 v[60:61], v[60:61], v[78:79] op_sel_hi:[1,0]
	v_pk_mul_f32 v[58:59], v[58:59], v[78:79] op_sel_hi:[1,0]
	v_pk_mul_f32 v[56:57], v[56:57], v[78:79] op_sel_hi:[1,0]
; __device__ __forceinline__ float ex2(float x) { return __builtin_amdgcn_exp2f(x); }
; template <bool FOX> ...
;     ...
;       float mx = fmaxf(fmaxf(st[qt][0], st[qt][1]), fmaxf(st[qt][2], st[qt][3]));
; #pragma unroll
;       for (int r = 4; r < 16; r += 4) mx = fmaxf(fmaxf(mx, st[qt][r]), fmaxf(fmaxf(st[qt][r + 1], st[qt][r + 2]), st[qt][r + 3]));
;       mx = xmax32(mx);
;       const float mnew = fmaxf(mrun[qt], mx);
;       const float alpha = ex2(mrun[qt] - mnew);
;       mrun[qt] = mnew;
;       float ps0 = 0.f, ps1 = 0.f;
; #pragma unroll
;       for (int r = 0; r < 16; r += 2) {
;         float p0 = ex2(st[qt][r] - mnew), p1 = ex2(st[qt][r + 1] - mnew);
;         ps0 += p0; ps1 += p1;
;         st[qt][r] = p0; st[qt][r + 1] = p1;
;       }
;       lrun[qt] = lrun[qt] * alpha + (ps0 + ps1);
; #pragma unroll
;       for (int dt = 0; dt < 2; ++dt) o[dt][qt] = o[dt][qt] * alpha;
; #pragma unroll
;       for (int ks = 0; ks < 2; ++ks) {
;         union { bf16x8 v; uint32_t w[4]; } u;
; #pragma unroll
;         for (int e = 0; e < 4; ++e) u.w[e] = pack2(st[qt][8 * ks + 2 * e], st[qt][8 * ks + 2 * e + 1]);
;         bp[qt][ks] = u.v;
;       }
;     }
; #pragma unroll
;     for (int dt = 0; dt < 2; ++dt)
; #pragma unroll
;       for (int qt = 0; qt < 2; ++qt)
; #pragma unroll
;         for (int ks = 0; ks < 2; ++ks) o[dt][qt] = mfma32(av[dt][ks], bp[qt][ks], o[dt][qt]);
	v_pk_mul_f32 v[54:55], v[54:55], v[78:79] op_sel_hi:[1,0]
	v_pk_mul_f32 v[52:53], v[52:53], v[78:79] op_sel_hi:[1,0]
	v_pk_mul_f32 v[50:51], v[50:51], v[78:79] op_sel_hi:[1,0]
	v_pk_mul_f32 v[48:49], v[48:49], v[78:79] op_sel_hi:[1,0]
	v_pk_mul_f32 v[46:47], v[46:47], v[78:79] op_sel_hi:[1,0]
	v_pk_mul_f32 v[44:45], v[44:45], v[78:79] op_sel_hi:[1,0]
	v_pk_mul_f32 v[42:43], v[42:43], v[78:79] op_sel_hi:[1,0]
	v_pk_mul_f32 v[40:41], v[40:41], v[78:79] op_sel_hi:[1,0]
	v_pk_mul_f32 v[38:39], v[38:39], v[78:79] op_sel_hi:[1,0]
	v_pk_mul_f32 v[36:37], v[36:37], v[78:79] op_sel_hi:[1,0]
	v_pk_mul_f32 v[34:35], v[34:35], v[78:79] op_sel_hi:[1,0]
	v_pk_mul_f32 v[32:33], v[32:33], v[78:79] op_sel_hi:[1,0]
	v_max_f32_e32 v79, v175, v195
	v_exp_f32_e32 v82, v65
	v_sub_f32_e32 v65, v176, v186
	v_max3_f32 v79, v193, v194, v79
	v_max3_f32 v81, v196, v179, v197
	v_exp_f32_e32 v84, v65
	v_sub_f32_e32 v65, v83, v186
	v_max3_f32 v79, v79, v177, v81
	v_max3_f32 v81, v73, v198, v75
	v_exp_f32_e32 v88, v65
	v_sub_f32_e32 v65, v178, v186
	v_max3_f32 v79, v79, v181, v81
	v_max3_f32 v81, v77, v189, v199
	v_exp_f32_e32 v94, v65
	v_sub_f32_e32 v65, v85, v186
	v_max3_f32 v79, v79, v188, v81
	v_exp_f32_e32 v86, v65
	v_sub_f32_e32 v65, v180, v186
	v_mov_b32_e32 v81, v79
	v_exp_f32_e32 v92, v65
	v_sub_f32_e32 v65, v87, v186
	v_permlane32_swap_b32_e32 v79, v81
	v_exp_f32_e32 v174, v65
	v_sub_f32_e32 v65, v187, v186
	v_max3_f32 v187, v173, v79, v81
	v_exp_f32_e32 v176, v65
	v_sub_f32_e32 v65, v89, v186
	v_sub_f32_e32 v79, v173, v187
	v_exp_f32_e32 v178, v65
	v_sub_f32_e32 v65, v90, v186
	v_exp_f32_e32 v79, v79
	v_exp_f32_e32 v180, v65
	v_sub_f32_e32 v65, v91, v186
	v_exp_f32_e32 v72, v65
	v_sub_f32_e32 v65, v190, v186
	v_exp_f32_e32 v74, v65
	v_sub_f32_e32 v65, v93, v186
	v_sub_f32_e32 v87, v195, v187
	v_sub_f32_e32 v91, v179, v187
	v_exp_f32_e32 v76, v65
	v_sub_f32_e32 v65, v192, v186
	v_exp_f32_e32 v89, v87
	v_sub_f32_e32 v87, v177, v187
	v_exp_f32_e32 v93, v91
	v_sub_f32_e32 v91, v197, v187
	v_sub_f32_e32 v73, v73, v187
	v_mov_b32_e32 v192, v79
	v_sub_f32_e32 v64, v95, v186
	v_sub_f32_e32 v81, v193, v187
	v_sub_f32_e32 v83, v194, v187
	v_sub_f32_e32 v85, v175, v187
	v_exp_f32_e32 v95, v87
	v_sub_f32_e32 v87, v196, v187
	v_exp_f32_e32 v175, v91
	v_sub_f32_e32 v91, v181, v187
	v_exp_f32_e32 v179, v73
	v_sub_f32_e32 v73, v198, v187
	v_pk_mul_f32 v[30:31], v[30:31], v[192:193] op_sel_hi:[1,0]
	v_pk_mul_f32 v[28:29], v[28:29], v[192:193] op_sel_hi:[1,0]
	v_pk_mul_f32 v[26:27], v[26:27], v[192:193] op_sel_hi:[1,0]
	v_pk_mul_f32 v[24:25], v[24:25], v[192:193] op_sel_hi:[1,0]
	v_pk_mul_f32 v[22:23], v[22:23], v[192:193] op_sel_hi:[1,0]
	v_pk_mul_f32 v[20:21], v[20:21], v[192:193] op_sel_hi:[1,0]
	v_pk_mul_f32 v[18:19], v[18:19], v[192:193] op_sel_hi:[1,0]
	v_pk_mul_f32 v[16:17], v[16:17], v[192:193] op_sel_hi:[1,0]
	v_pk_mul_f32 v[14:15], v[14:15], v[192:193] op_sel_hi:[1,0]
	v_pk_mul_f32 v[12:13], v[12:13], v[192:193] op_sel_hi:[1,0]
	v_pk_mul_f32 v[10:11], v[10:11], v[192:193] op_sel_hi:[1,0]
	v_pk_mul_f32 v[8:9], v[8:9], v[192:193] op_sel_hi:[1,0]
	v_pk_mul_f32 v[6:7], v[6:7], v[192:193] op_sel_hi:[1,0]
	v_pk_mul_f32 v[4:5], v[4:5], v[192:193] op_sel_hi:[1,0]
	v_pk_mul_f32 v[2:3], v[2:3], v[192:193] op_sel_hi:[1,0]
	v_pk_mul_f32 v[0:1], v[0:1], v[192:193] op_sel_hi:[1,0]
	v_cvt_pk_bf16_f32 v68, v80, v82
	v_cvt_pk_bf16_f32 v69, v84, v88
	v_cvt_pk_bf16_f32 v70, v94, v86
	v_cvt_pk_bf16_f32 v71, v92, v174
	v_exp_f32_e32 v81, v81
	v_exp_f32_e32 v83, v83
	v_exp_f32_e32 v85, v85
	v_exp_f32_e32 v87, v87
	v_exp_f32_e32 v177, v91
	v_exp_f32_e32 v181, v73
	v_sub_f32_e32 v73, v75, v187
	v_sub_f32_e32 v75, v188, v187
	s_waitcnt vmcnt(3)
	v_mfma_f32_32x32x16_bf16 v[48:63], v[158:161], v[68:71], v[48:63]
	v_sub_f32_e32 v91, v189, v187
	v_cvt_pk_bf16_f32 v188, v81, v83
	v_cvt_pk_bf16_f32 v189, v85, v89
	v_cvt_pk_bf16_f32 v190, v95, v87
	v_cvt_pk_bf16_f32 v191, v93, v175
	v_add_f32_e64 v80, v80, 0
	v_add_f32_e64 v81, v81, 0
	v_add_f32_e64 v82, v82, 0
	v_add_f32_e64 v83, v83, 0
	v_mfma_f32_32x32x16_bf16 v[16:31], v[158:161], v[188:191], v[16:31]
	v_exp_f32_e32 v73, v73
	v_sub_f32_e32 v77, v77, v187
	v_sub_f32_e32 v158, v199, v187
	v_pk_add_f32 v[80:81], v[84:85], v[80:81]
	v_pk_add_f32 v[82:83], v[88:89], v[82:83]
	v_exp_f32_e32 v90, v65
	v_exp_f32_e32 v172, v64
	s_waitcnt vmcnt(1)
	v_mfma_f32_32x32x16_bf16 v[32:47], v[150:153], v[68:71], v[32:47]
	v_cvt_pk_bf16_f32 v64, v176, v178
	v_cvt_pk_bf16_f32 v65, v180, v72
	v_cvt_pk_bf16_f32 v66, v74, v76
	v_cvt_pk_bf16_f32 v67, v90, v172
	v_exp_f32_e32 v75, v75
	v_exp_f32_e32 v77, v77
	v_exp_f32_e32 v91, v91
	v_mfma_f32_32x32x16_bf16 v[0:15], v[150:153], v[188:191], v[0:15]
	v_exp_f32_e32 v173, v158
	v_cvt_pk_bf16_f32 v158, v177, v179
	v_cvt_pk_bf16_f32 v159, v181, v73
	v_cvt_pk_bf16_f32 v160, v75, v77
	v_cvt_pk_bf16_f32 v161, v91, v173
	v_pk_add_f32 v[80:81], v[94:95], v[80:81]
	v_pk_add_f32 v[68:69], v[86:87], v[82:83]
	v_mfma_f32_32x32x16_bf16 v[48:63], v[154:157], v[64:67], v[48:63]
	v_add_f32_e64 v70, v92, v80
	v_add_f32_e64 v71, v93, v81
	v_add_f32_e64 v68, v174, v68
	v_add_f32_e64 v69, v175, v69
	v_add_f32_e64 v70, v176, v70
	v_add_f32_e64 v71, v177, v71
	v_pk_add_f32 v[68:69], v[178:179], v[68:69]
	v_pk_add_f32 v[70:71], v[180:181], v[70:71]
	v_lshl_add_u64 v[170:171], v[170:171], 0, s[68:69]
	s_add_i32 s11, s11, 1
	v_mfma_f32_32x32x16_bf16 v[16:31], v[154:157], v[158:161], v[16:31]
	s_andn2_b64 vcc, exec, s[6:7]
	v_add_u32_e32 v185, 32, v185
	s_waitcnt vmcnt(0)
	v_mfma_f32_32x32x16_bf16 v[32:47], v[146:149], v[64:67], v[32:47]
	v_add_f32_e64 v64, v72, v68
	v_add_f32_e64 v65, v73, v69
	v_add_f32_e64 v66, v74, v70
	v_add_f32_e64 v67, v75, v71
	v_add_f32_e64 v64, v76, v64
	v_add_f32_e64 v65, v77, v65
	v_pk_add_f32 v[66:67], v[90:91], v[66:67]
	v_pk_add_f32 v[64:65], v[172:173], v[64:65]
	s_nop 0
	v_pk_add_f32 v[64:65], v[66:67], v[64:65]
	v_mfma_f32_32x32x16_bf16 v[0:15], v[146:149], v[158:161], v[0:15]
	v_fma_f32 v164, v164, v78, v64
	v_fma_f32 v165, v165, v79, v65
	s_cbranch_vccz .LBB0_495
	v_mov_b32_e32 v172, v186
	v_mov_b32_e32 v173, v187
	s_branch .LBB0_499

; __device__ __forceinline__ float ex2(float x) { return __builtin_amdgcn_exp2f(x); }
; template <bool FOX> ...
;     ...
;       float mx = fmaxf(fmaxf(st[qt][0], st[qt][1]), fmaxf(st[qt][2], st[qt][3]));
; #pragma unroll
;       for (int r = 4; r < 16; r += 4) mx = fmaxf(fmaxf(mx, st[qt][r]), fmaxf(fmaxf(st[qt][r + 1], st[qt][r + 2]), st[qt][r + 3]));
;       mx = xmax32(mx);
;       const float mnew = fmaxf(mrun[qt], mx);
;       const float alpha = ex2(mrun[qt] - mnew);
;       mrun[qt] = mnew;
;       float ps0 = 0.f, ps1 = 0.f;
; #pragma unroll
;       for (int r = 0; r < 16; r += 2) {
;         float p0 = ex2(st[qt][r] - mnew), p1 = ex2(st[qt][r + 1] - mnew);
;         ps0 += p0; ps1 += p1;
;         st[qt][r] = p0; st[qt][r + 1] = p1;
;       }
;       lrun[qt] = lrun[qt] * alpha + (ps0 + ps1);
; #pragma unroll
;       for (int dt = 0; dt < 2; ++dt) o[dt][qt] = o[dt][qt] * alpha;
; #pragma unroll
;       for (int ks = 0; ks < 2; ++ks) {
;         union { bf16x8 v; uint32_t w[4]; } u;
; #pragma unroll
;         for (int e = 0; e < 4; ++e) u.w[e] = pack2(st[qt][8 * ks + 2 * e], st[qt][8 * ks + 2 * e + 1]);
;         bp[qt][ks] = u.v;
;       }
;     }
.LBB0_512:
	s_nop 7
	v_max_f32_e32 v182, v98, v99
	v_max3_f32 v182, v96, v97, v182
	v_max3_f32 v194, v101, v102, v103
	v_max3_f32 v182, v182, v100, v194
	v_max3_f32 v194, v105, v106, v107
	v_max3_f32 v182, v182, v104, v194
	v_max3_f32 v194, v109, v110, v111
	v_max3_f32 v182, v182, v108, v194
	v_mov_b32_e32 v194, v182
	s_nop 1
	v_permlane32_swap_b32_e32 v182, v194
	v_max3_f32 v182, v185, v182, v194
	v_pk_add_f32 v[96:97], v[96:97], v[182:183] op_sel_hi:[1,0] neg_lo:[0,1] neg_hi:[0,1]
	v_pk_add_f32 v[98:99], v[98:99], v[182:183] op_sel_hi:[1,0] neg_lo:[0,1] neg_hi:[0,1]
	v_pk_add_f32 v[100:101], v[100:101], v[182:183] op_sel_hi:[1,0] neg_lo:[0,1] neg_hi:[0,1]
	v_pk_add_f32 v[102:103], v[102:103], v[182:183] op_sel_hi:[1,0] neg_lo:[0,1] neg_hi:[0,1]
	v_exp_f32_e32 v194, v96
	v_exp_f32_e32 v196, v97
	v_exp_f32_e32 v198, v98
	v_exp_f32_e32 v200, v99
	v_exp_f32_e32 v202, v100
	v_exp_f32_e32 v204, v101
	v_exp_f32_e32 v206, v102
	v_exp_f32_e32 v208, v103
	v_pk_add_f32 v[96:97], v[104:105], v[182:183] op_sel_hi:[1,0] neg_lo:[0,1] neg_hi:[0,1]
	v_pk_add_f32 v[106:107], v[106:107], v[182:183] op_sel_hi:[1,0] neg_lo:[0,1] neg_hi:[0,1]
	v_pk_add_f32 v[108:109], v[108:109], v[182:183] op_sel_hi:[1,0] neg_lo:[0,1] neg_hi:[0,1]
	v_pk_add_f32 v[110:111], v[110:111], v[182:183] op_sel_hi:[1,0] neg_lo:[0,1] neg_hi:[0,1]
	v_max_f32_e32 v104, v82, v83
	v_max3_f32 v104, v80, v81, v104
	v_max3_f32 v105, v85, v86, v87
	v_max3_f32 v104, v104, v84, v105
	v_max3_f32 v105, v89, v90, v91
	v_max3_f32 v104, v104, v88, v105
	v_max3_f32 v105, v93, v94, v95
	v_max3_f32 v104, v104, v92, v105
	v_mov_b32_e32 v105, v104
	s_nop 1
	v_permlane32_swap_b32_e32 v104, v105
	v_max3_f32 v104, v113, v104, v105
	v_exp_f32_e32 v210, v96
	v_exp_f32_e32 v212, v97
	v_exp_f32_e32 v106, v106
	v_exp_f32_e32 v214, v107
	v_exp_f32_e32 v108, v108
	v_exp_f32_e32 v216, v109
	v_exp_f32_e32 v110, v110
	v_exp_f32_e32 v234, v111
	v_pk_add_f32 v[80:81], v[80:81], v[104:105] op_sel_hi:[1,0] neg_lo:[0,1] neg_hi:[0,1]
	v_pk_add_f32 v[82:83], v[82:83], v[104:105] op_sel_hi:[1,0] neg_lo:[0,1] neg_hi:[0,1]
	v_pk_add_f32 v[84:85], v[84:85], v[104:105] op_sel_hi:[1,0] neg_lo:[0,1] neg_hi:[0,1]
	v_pk_add_f32 v[86:87], v[86:87], v[104:105] op_sel_hi:[1,0] neg_lo:[0,1] neg_hi:[0,1]
	v_pk_add_f32 v[88:89], v[88:89], v[104:105] op_sel_hi:[1,0] neg_lo:[0,1] neg_hi:[0,1]
	v_pk_add_f32 v[90:91], v[90:91], v[104:105] op_sel_hi:[1,0] neg_lo:[0,1] neg_hi:[0,1]
	v_pk_add_f32 v[92:93], v[92:93], v[104:105] op_sel_hi:[1,0] neg_lo:[0,1] neg_hi:[0,1]
	v_pk_add_f32 v[94:95], v[94:95], v[104:105] op_sel_hi:[1,0] neg_lo:[0,1] neg_hi:[0,1]
	v_exp_f32_e32 v195, v80
	v_exp_f32_e32 v197, v81
	v_exp_f32_e32 v199, v82
	v_exp_f32_e32 v201, v83
	v_exp_f32_e32 v203, v84
	v_exp_f32_e32 v205, v85
	v_exp_f32_e32 v207, v86
	v_exp_f32_e32 v209, v87
	v_exp_f32_e32 v211, v88
	v_exp_f32_e32 v213, v89
	v_exp_f32_e32 v107, v90
	v_exp_f32_e32 v215, v91
	v_exp_f32_e32 v109, v92
	v_exp_f32_e32 v217, v93
	v_exp_f32_e32 v111, v94
	v_exp_f32_e32 v235, v95
	v_sub_f32_e32 v185, v185, v182
	v_pk_add_f32 v[80:81], v[194:195], 0 op_sel_hi:[1,0]
	v_pk_add_f32 v[82:83], v[196:197], 0 op_sel_hi:[1,0]
	v_exp_f32_e32 v236, v185
	v_pk_add_f32 v[80:81], v[198:199], v[80:81]
	v_pk_add_f32 v[82:83], v[200:201], v[82:83]
	v_pk_add_f32 v[80:81], v[202:203], v[80:81]
	v_pk_add_f32 v[82:83], v[204:205], v[82:83]
	v_pk_add_f32 v[80:81], v[206:207], v[80:81]
	v_pk_add_f32 v[82:83], v[208:209], v[82:83]
	v_sub_f32_e32 v105, v113, v104
	v_pk_add_f32 v[80:81], v[210:211], v[80:81]
	v_pk_add_f32 v[82:83], v[212:213], v[82:83]
	v_pk_mul_f32 v[62:63], v[62:63], v[236:237] op_sel_hi:[1,0]
	v_pk_mul_f32 v[60:61], v[60:61], v[236:237] op_sel_hi:[1,0]
	v_pk_mul_f32 v[58:59], v[58:59], v[236:237] op_sel_hi:[1,0]
	v_pk_mul_f32 v[56:57], v[56:57], v[236:237] op_sel_hi:[1,0]
	v_pk_mul_f32 v[54:55], v[54:55], v[236:237] op_sel_hi:[1,0]
	v_pk_mul_f32 v[52:53], v[52:53], v[236:237] op_sel_hi:[1,0]
	v_pk_mul_f32 v[50:51], v[50:51], v[236:237] op_sel_hi:[1,0]
	v_pk_mul_f32 v[48:49], v[48:49], v[236:237] op_sel_hi:[1,0]
	v_pk_mul_f32 v[46:47], v[46:47], v[236:237] op_sel_hi:[1,0]
	v_pk_mul_f32 v[44:45], v[44:45], v[236:237] op_sel_hi:[1,0]
	v_pk_mul_f32 v[42:43], v[42:43], v[236:237] op_sel_hi:[1,0]
	v_pk_mul_f32 v[40:41], v[40:41], v[236:237] op_sel_hi:[1,0]
	v_pk_mul_f32 v[38:39], v[38:39], v[236:237] op_sel_hi:[1,0]
	v_pk_mul_f32 v[36:37], v[36:37], v[236:237] op_sel_hi:[1,0]
	v_pk_mul_f32 v[34:35], v[34:35], v[236:237] op_sel_hi:[1,0]
	v_pk_mul_f32 v[32:33], v[32:33], v[236:237] op_sel_hi:[1,0]
	v_exp_f32_e32 v237, v105
	v_pk_add_f32 v[80:81], v[106:107], v[80:81]
	v_pk_add_f32 v[82:83], v[214:215], v[82:83]
	v_pk_add_f32 v[80:81], v[108:109], v[80:81]
	v_pk_add_f32 v[82:83], v[216:217], v[82:83]
	v_pk_add_f32 v[80:81], v[110:111], v[80:81]
	v_pk_add_f32 v[82:83], v[234:235], v[82:83]
	v_cvt_pk_bf16_f32 v100, v194, v196
	v_cvt_pk_bf16_f32 v101, v198, v200
	v_cvt_pk_bf16_f32 v102, v202, v204
	v_cvt_pk_bf16_f32 v103, v206, v208
	v_cvt_pk_bf16_f32 v84, v195, v197
	s_nop 0
	v_pk_add_f32 v[80:81], v[80:81], v[82:83]
	v_cvt_pk_bf16_f32 v85, v199, v201
	v_cvt_pk_bf16_f32 v86, v203, v205
	v_cvt_pk_bf16_f32 v87, v207, v209
	s_waitcnt vmcnt(3)
; template <bool FOX> ...
;     ...
;       lrun[qt] = lrun[qt] * alpha + (ps0 + ps1);
; #pragma unroll
;       for (int dt = 0; dt < 2; ++dt) o[dt][qt] = o[dt][qt] * alpha;
; #pragma unroll
;       for (int ks = 0; ks < 2; ++ks) {
;         union { bf16x8 v; uint32_t w[4]; } u;
; #pragma unroll
;         for (int e = 0; e < 4; ++e) u.w[e] = pack2(st[qt][8 * ks + 2 * e], st[qt][8 * ks + 2 * e + 1]);
;         bp[qt][ks] = u.v;
;       }
;     }
; #pragma unroll
;     for (int dt = 0; dt < 2; ++dt)
; #pragma unroll
;       for (int qt = 0; qt < 2; ++qt)
; #pragma unroll
;         for (int ks = 0; ks < 2; ++ks) o[dt][qt] = mfma32(av[dt][ks], bp[qt][ks], o[dt][qt]);
	v_mfma_f32_32x32x16_bf16 v[48:63], v[174:177], v[100:103], v[48:63]
	v_fma_f32 v188, v188, v236, v80
	v_fma_f32 v189, v189, v237, v81
	v_mov_b32_e32 v80, v237
	v_mul_f32_e64 v30, v30, v80
	v_mul_f32_e64 v31, v31, v80
	v_pk_mul_f32 v[28:29], v[28:29], v[80:81] op_sel_hi:[1,0]
	v_pk_mul_f32 v[26:27], v[26:27], v[80:81] op_sel_hi:[1,0]
	v_pk_mul_f32 v[24:25], v[24:25], v[80:81] op_sel_hi:[1,0]
	v_pk_mul_f32 v[22:23], v[22:23], v[80:81] op_sel_hi:[1,0]
	v_pk_mul_f32 v[20:21], v[20:21], v[80:81] op_sel_hi:[1,0]
	v_pk_mul_f32 v[18:19], v[18:19], v[80:81] op_sel_hi:[1,0]
	v_pk_mul_f32 v[16:17], v[16:17], v[80:81] op_sel_hi:[1,0]
	v_pk_mul_f32 v[14:15], v[14:15], v[80:81] op_sel_hi:[1,0]
	v_pk_mul_f32 v[12:13], v[12:13], v[80:81] op_sel_hi:[1,0]
	v_pk_mul_f32 v[10:11], v[10:11], v[80:81] op_sel_hi:[1,0]
	v_pk_mul_f32 v[8:9], v[8:9], v[80:81] op_sel_hi:[1,0]
	v_pk_mul_f32 v[6:7], v[6:7], v[80:81] op_sel_hi:[1,0]
	v_pk_mul_f32 v[4:5], v[4:5], v[80:81] op_sel_hi:[1,0]
	v_pk_mul_f32 v[2:3], v[2:3], v[80:81] op_sel_hi:[1,0]
	v_pk_mul_f32 v[0:1], v[0:1], v[80:81] op_sel_hi:[1,0]
	v_mfma_f32_32x32x16_bf16 v[16:31], v[174:177], v[84:87], v[16:31]
	v_cvt_pk_bf16_f32 v96, v210, v212
	v_cvt_pk_bf16_f32 v97, v106, v214
	v_cvt_pk_bf16_f32 v98, v108, v216
	v_cvt_pk_bf16_f32 v99, v110, v234
	v_cvt_pk_bf16_f32 v80, v211, v213
	v_cvt_pk_bf16_f32 v81, v107, v215
	v_cvt_pk_bf16_f32 v82, v109, v217
	s_waitcnt vmcnt(1)
	v_mfma_f32_32x32x16_bf16 v[32:47], v[166:169], v[100:103], v[32:47]
	v_cvt_pk_bf16_f32 v83, v111, v235
	s_add_i32 s10, s10, 32
	v_lshl_add_u64 v[190:191], v[190:191], 0, s[68:69]
	v_lshl_add_u64 v[192:193], v[192:193], 0, s[86:87]
	s_cmp_eq_u32 s8, s9
	v_mfma_f32_32x32x16_bf16 v[0:15], v[166:169], v[84:87], v[0:15]
	v_mfma_f32_32x32x16_bf16 v[48:63], v[170:173], v[96:99], v[48:63]
	v_mfma_f32_32x32x16_bf16 v[16:31], v[170:173], v[80:83], v[16:31]
	s_waitcnt vmcnt(0)
	v_mfma_f32_32x32x16_bf16 v[32:47], v[162:165], v[96:99], v[32:47]
	v_mfma_f32_32x32x16_bf16 v[0:15], v[162:165], v[80:83], v[0:15]
	s_cbranch_scc1 .LBB0_505
	v_mov_b32_e32 v185, v182
	v_mov_b32_e32 v113, v104
	s_branch .LBB0_508
